# phase 6 chunk scan: operands fetched two chunks ahead (loop unrolled by two, two register sets, one counted wait before the LDS store)
# speedup vs baseline: 1.0094x; 1.0081x over previous
; #define LAS __attribute__((address_space(3)))
; __device__ __forceinline__ unsigned pk2(float lo, float hi) { const f32x2 v = {lo, hi}; const bf16x2_hw b = __builtin_convertvector(v, bf16x2_hw); return __builtin_bit_cast(unsigned, b); }
; __device__ __forceinline__ void scan_phase(const Params& p, int bid, int nblk, LAS unsigned char* lds) {
;     ...
;             { u32x2 w; w.x = pk2(sacc[0], sacc[1]); w.y = pk2(sacc[2], sacc[3]); *(LAS u32x2*)(lds + SC_ST + fr * 272 + (wid * 16 + fq * 4) * 2) = w; }
;             if (n + 1 < 32) lstore(cur ^ 1);
;             __syncthreads();
;         }
; #pragma unroll
;         for (int j = 0; j < 4; ++j) p.out[O_DP + ((size_t)bh * 128 + wid * 16 + fq * 4 + j) * 128 + sl * 16 + fr] = sacc[j];
.LBB0_1067:
	s_ashr_i32 s25, s24, 31
	s_nop 5
	v_cvt_pk_bf16_f32 v8, v4, v5
	v_cvt_pk_bf16_f32 v9, v6, v7
	s_lshl_b64 s[8:9], s[24:25], 16
	ds_write_b64 v106, v[8:9]
	v_lshl_add_u64 v[8:9], v[56:57], 0, s[8:9]
	s_lshl_b32 s16, s34, 2
	v_lshl_add_u64 v[8:9], v[8:9], 0, s[16:17]
	v_lshl_add_u64 v[8:9], v[8:9], 0, v[50:51]
	v_add_co_u32_e32 v8, vcc, 0x4400000, v8
	s_add_i32 s41, s41, s96
	s_add_i32 s36, s36, s37
	v_addc_co_u32_e32 v9, vcc, 0, v9, vcc
	s_cmpk_gt_i32 s41, 0xff
	s_waitcnt lgkmcnt(0)
	s_barrier
	global_store_dword v[8:9], v4, off
	global_store_dword v[8:9], v5, off offset:512
	global_store_dword v[8:9], v6, off offset:1024
	global_store_dword v[8:9], v7, off offset:1536
	s_cbranch_scc1 .LBB0_1096
	s_waitcnt vmcnt(0)

; #define LAS __attribute__((address_space(3)))
; __device__ __forceinline__ void scan_phase(const Params& p, int bid, int nblk, LAS unsigned char* lds) {
;     ...
;         __syncthreads();
;         gload(0);
;         for (int i = tid; i < 4352 / 4; i += 512) *(LAS unsigned*)(lds + SC_ST + i * 4) = 0u;
;         lstore(0);
;         f32x4 sacc = (f32x4){0.f, 0.f, 0.f, 0.f};
;         const float cdall = cdv[bh * 32 + (lane & 31)];
;         __syncthreads();
;         for (int n = 0; n < 32; ++n) {
;             const int cur = n & 1; LAS unsigned char* B = lds + cur * SB_SIZE;
;             if (n + 1 < 32) gload(n + 1);
.LBB0_1076:
	s_or_b64 exec, exec, s[28:29]
	s_waitcnt vmcnt(6)
	ds_write_b128 v96, v[4:7]
	s_waitcnt vmcnt(5)
	ds_write_b128 v96, v[8:11] offset:17408
	s_waitcnt vmcnt(4)
	ds_write_b128 v97, v[12:15] offset:34816
	s_waitcnt vmcnt(3)
	ds_write_b128 v98, v[16:19]
	s_waitcnt vmcnt(2)
	ds_write_b128 v98, v[20:23] offset:17408
	s_waitcnt vmcnt(1)
	ds_write_b128 v99, v[24:27] offset:34816
	s_waitcnt vmcnt(0)
	ds_write_b128 v97, v[28:31] offset:53248
	s_and_saveexec_b64 s[8:9], s[6:7]
	ds_write_b128 v100, v[0:3] offset:62464
	s_or_b64 exec, exec, s[8:9]
	v_or_b32_e32 v4, s26, v74
	v_ashrrev_i32_e32 v5, 31, v4
	v_lshl_add_u64 v[4:5], v[4:5], 2, s[10:11]
	global_load_dword v69, v[4:5], off
	s_bfe_u32 s8, s36, 0x30002
	s_lshl_b32 s26, s8, 10
	s_lshl_b32 s27, s8, 7
	s_and_b32 s8, s16, 7
	s_lshl_b32 s16, s8, 6
	s_lshl_b32 s8, s24, 9
	s_lshl_b32 s34, s42, 4
	s_and_b32 s8, s8, 0xe00
	s_add_u32 s8, s12, s8
	s_addc_u32 s9, s13, 0
	s_lshl_b32 s28, s42, 6
	s_add_u32 s8, s8, s28
	s_addc_u32 s9, s9, 0
	v_lshl_add_u64 v[70:71], s[8:9], 0, v[50:51]
	s_lshl_b32 s8, s25, 8
	s_add_i32 s26, s26, s8
	s_and_b32 s8, s26, 0xfffff800
	v_or_b32_e32 v107, s8, v95
	s_lshl_b32 s8, s25, 5
	s_add_i32 s8, s27, s8
	s_ashr_i32 s9, s8, 31
	s_lshl_b64 s[26:27], s[8:9], 15
	s_or_b32 s26, s26, s16
	v_lshl_add_u64 v[72:73], v[66:67], 0, s[26:27]
	s_lshl_b64 s[26:27], s[8:9], 14
	s_add_u32 s26, s14, s26
	s_addc_u32 s27, s15, s27
	s_lshl_b64 s[8:9], s[8:9], 13
	s_add_u32 s28, s38, s8
	v_mov_b32_e32 v4, 0
	s_addc_u32 s29, s39, s9
	s_mov_b32 s25, 0
	s_mov_b32 s35, 0
	v_mov_b32_e32 v5, v4
	v_mov_b32_e32 v6, v4
	v_mov_b32_e32 v7, v4
	s_mov_b64 s[44:45], 0x2000
	v_lshl_add_u64 v[24:25], s[26:27], 0, v[48:49]
	v_add_co_u32_e32 v16, vcc, 0xe53d000, v24
	v_lshl_add_u64 v[32:33], s[28:29], 0, v[48:49]
	s_nop 0
	v_addc_co_u32_e32 v17, vcc, 0, v25, vcc
	v_add_co_u32_e32 v18, vcc, 0xf53d000, v24
	s_nop 1
	v_addc_co_u32_e32 v19, vcc, 0, v25, vcc
	global_load_dwordx4 v[8:11], v[16:17], off
	global_load_dwordx4 v[12:15], v[18:19], off
	v_add_co_u32_e32 v16, vcc, 0x1053d000, v24
	s_nop 1
	v_addc_co_u32_e32 v17, vcc, 0, v25, vcc
	v_add_co_u32_e32 v20, vcc, 0xe53f000, v24
	s_nop 1
	v_addc_co_u32_e32 v21, vcc, 0, v25, vcc
	v_add_co_u32_e32 v26, vcc, 0xf53f000, v24
	global_load_dwordx4 v[16:19], v[16:17], off
	s_nop 0
	global_load_dwordx4 v[20:23], v[20:21], off
	v_addc_co_u32_e32 v27, vcc, 0, v25, vcc
	v_add_co_u32_e32 v28, vcc, 0x1053f000, v24
	s_nop 1
	v_addc_co_u32_e32 v29, vcc, 0, v25, vcc
	global_load_dwordx4 v[24:27], v[26:27], off
	s_nop 0
	global_load_dwordx4 v[28:31], v[28:29], off
	s_nop 0
	global_load_dwordx4 v[32:35], v[32:33], off
	s_and_saveexec_b64 s[8:9], s[6:7]
	s_cbranch_execz .Lsc_pro
	global_load_dwordx4 v[0:3], v[72:73], off
.Lsc_pro:
	s_or_b64 exec, exec, s[8:9]
	s_waitcnt lgkmcnt(0)
	s_barrier
	s_branch .LBB0_1080

; #define LAS __attribute__((address_space(3)))
; __device__ __forceinline__ void scan_phase(const Params& p, int bid, int nblk, LAS unsigned char* lds) {
;     ...
;         auto gload = [&](int n) {
;             const size_t it = (size_t)(bh * 32 + n);
; #pragma unroll
;             for (int i = 0; i < 2; ++i) { const int ch = tid + 512 * i; r_wd[i] = *(const u32x4*)(wdc + it * 8192 + ch * 8); r_qd[i] = *(const u32x4*)(qd + it * 8192 + ch * 8); r_kt[i] = *(const u32x4*)(kt + it * 8192 + ch * 8); }
;             r_qk = *(const u32x4*)(qk + it * 4096 + tid * 8);
;             if (tid < 256) r_ub = *(const u32x4*)(ub + it * 8192 + (tid >> 2) * 128 + sl * 16 + (tid & 3) * 4);
;         };
;     ...
;         for (int n = 0; n < 32; ++n) {
;             const int cur = n & 1; LAS unsigned char* B = lds + cur * SB_SIZE;
;             if (n + 1 < 32) gload(n + 1);
.LBB0_1080_o:
	s_cmp_lg_u32 s35, 0
	s_cbranch_scc1 .Lscan_nw_o
	s_waitcnt vmcnt(7)
.Lscan_nw_o:
	s_and_b64 vcc, exec, s[18:19]
	s_cbranch_vccnz .Lscan_skipld_o
	v_lshl_add_u64 v[24:25], s[26:27], 0, v[48:49]
	v_add_co_u32_e32 v16, vcc, 0xe541000, v24
	v_lshl_add_u64 v[32:33], s[28:29], 0, v[48:49]
	s_nop 0
	v_addc_co_u32_e32 v17, vcc, 0, v25, vcc
	v_add_co_u32_e32 v18, vcc, 0xf541000, v24
	s_nop 1
	v_addc_co_u32_e32 v19, vcc, 0, v25, vcc
	global_load_dwordx4 v[8:11], v[16:17], off
	global_load_dwordx4 v[12:15], v[18:19], off
	v_add_co_u32_e32 v16, vcc, 0x10541000, v24
	s_nop 1
	v_addc_co_u32_e32 v17, vcc, 0, v25, vcc
	v_add_co_u32_e32 v20, vcc, 0xe543000, v24
	s_nop 1
	v_addc_co_u32_e32 v21, vcc, 0, v25, vcc
	v_add_co_u32_e32 v26, vcc, 0xf543000, v24
	global_load_dwordx4 v[16:19], v[16:17], off
	s_nop 0
	global_load_dwordx4 v[20:23], v[20:21], off
	v_addc_co_u32_e32 v27, vcc, 0, v25, vcc
	v_add_co_u32_e32 v28, vcc, 0x10543000, v24
	s_nop 1
	v_addc_co_u32_e32 v29, vcc, 0, v25, vcc
	global_load_dwordx4 v[24:27], v[26:27], off
	s_nop 0
	global_load_dwordx4 v[28:31], v[28:29], off
	s_nop 0
	v_lshl_add_u64 v[32:33], v[32:33], 0, s[44:45]
	global_load_dwordx4 v[32:35], v[32:33], off
	s_and_saveexec_b64 s[8:9], s[6:7]
	s_cbranch_execz .LBB0_1082_o
	v_lshl_add_u64 v[0:1], v[72:73], 0, s[22:23]
	global_load_dwordx4 v[0:3], v[0:1], off

; #define LAS __attribute__((address_space(3)))
; __device__ __forceinline__ void scan_phase(const Params& p, int bid, int nblk, LAS unsigned char* lds) {
;     ...
;         auto gload = [&](int n) {
;             const size_t it = (size_t)(bh * 32 + n);
; #pragma unroll
;             for (int i = 0; i < 2; ++i) { const int ch = tid + 512 * i; r_wd[i] = *(const u32x4*)(wdc + it * 8192 + ch * 8); r_qd[i] = *(const u32x4*)(qd + it * 8192 + ch * 8); r_kt[i] = *(const u32x4*)(kt + it * 8192 + ch * 8); }
;             r_qk = *(const u32x4*)(qk + it * 4096 + tid * 8);
;             if (tid < 256) r_ub = *(const u32x4*)(ub + it * 8192 + (tid >> 2) * 128 + sl * 16 + (tid & 3) * 4);
;         };
;     ...
;             if (wid < 4) {
; #pragma unroll
;                 for (int j = 0; j < 4; ++j) acc[j] = *(const LAS float*)(B + SB_UB + ((tw * 16 + fq * 4 + j) * 16 + fr) * 4);
; #pragma unroll
;                 for (int kk = 0; kk < 4; ++kk) { const bf16x8 a = *(const LAS bf16x8*)(B + SB_WD + (tw * 16 + fr) * 272 + (kk * 32 + fq * 8) * 2); const bf16x8 bb = *(const LAS bf16x8*)(lds + SC_ST + fr * 272 + (kk * 32 + fq * 8) * 2);
;                     acc = __builtin_amdgcn_mfma_f32_16x16x32_bf16(a, bb, acc, 0, 0, 0); }
.Lscan_skipld_o:
	s_and_b32 s42, s35, 1
	s_mul_i32 s8, s42, 0x10400
	v_cndmask_b32_e64 v36, 0, 1, s[18:19]
	s_add_i32 s43, s8, 0
	v_readlane_b32 s16, v69, s35
	v_cmp_ne_u32_e64 s[8:9], 1, v36
	s_andn2_b64 vcc, exec, s[18:19]
	s_mov_b64 s[30:31], -1
	s_cbranch_vccnz .LBB0_1084_o
	v_add3_u32 v112, s43, v90, v84
	ds_read_b128 v[36:39], v112 offset:17408
	v_add_u32_e32 v116, v86, v84
	ds_read_b128 v[40:43], v112 offset:17472
	ds_read_b128 v[44:47], v116
	ds_read_b128 v[108:111], v116 offset:64
	s_mov_b64 s[30:31], 0
	s_waitcnt lgkmcnt(1)
	v_mfma_f32_16x16x32_bf16 v[36:39], v[36:39], v[44:47], 0
	ds_read_b128 v[44:47], v112 offset:17536
	ds_read_b128 v[112:115], v112 offset:17600
	s_waitcnt lgkmcnt(2)
	v_mfma_f32_16x16x32_bf16 v[36:39], v[40:43], v[108:111], v[36:39]
	ds_read_b128 v[40:43], v116 offset:128
	ds_read_b128 v[108:111], v116 offset:192
	s_waitcnt lgkmcnt(1)
	v_mfma_f32_16x16x32_bf16 v[36:39], v[44:47], v[40:43], v[36:39]
	s_waitcnt lgkmcnt(0)
	v_mfma_f32_16x16x32_bf16 v[36:39], v[112:115], v[108:111], v[36:39]
	v_lshl_add_u64 v[24:25], s[26:27], 0, v[48:49]
	v_add_co_u32_e32 v16, vcc, 0xe541000, v24
	v_lshl_add_u64 v[32:33], s[28:29], 0, v[48:49]
	s_nop 0
	v_addc_co_u32_e32 v17, vcc, 0, v25, vcc
	v_add_co_u32_e32 v18, vcc, 0xf541000, v24
	s_nop 1
	v_addc_co_u32_e32 v19, vcc, 0, v25, vcc
	global_load_dwordx4 v[8:11], v[16:17], off
	global_load_dwordx4 v[12:15], v[18:19], off
	v_add_co_u32_e32 v16, vcc, 0x10541000, v24
	s_nop 1
	v_addc_co_u32_e32 v17, vcc, 0, v25, vcc
	v_add_co_u32_e32 v20, vcc, 0xe543000, v24
	s_nop 1
	v_addc_co_u32_e32 v21, vcc, 0, v25, vcc
	v_add_co_u32_e32 v26, vcc, 0xf543000, v24
	global_load_dwordx4 v[16:19], v[16:17], off
	s_nop 0
	global_load_dwordx4 v[20:23], v[20:21], off
	v_addc_co_u32_e32 v27, vcc, 0, v25, vcc
	v_add_co_u32_e32 v28, vcc, 0x10543000, v24
	s_nop 1
	v_addc_co_u32_e32 v29, vcc, 0, v25, vcc
	global_load_dwordx4 v[24:27], v[26:27], off
	s_nop 0
	global_load_dwordx4 v[28:31], v[28:29], off
	s_nop 0
	v_lshl_add_u64 v[32:33], v[32:33], 0, s[44:45]
	global_load_dwordx4 v[32:35], v[32:33], off

; #define LAS __attribute__((address_space(3)))
; __device__ __forceinline__ unsigned pk2(float lo, float hi) { const f32x2 v = {lo, hi}; const bf16x2_hw b = __builtin_convertvector(v, bf16x2_hw); return __builtin_bit_cast(unsigned, b); }
; __device__ __forceinline__ void scan_phase(const Params& p, int bid, int nblk, LAS unsigned char* lds) {
;     ...
;         auto lstore = [&](int buf) {
;             LAS unsigned char* B = lds + buf * SB_SIZE;
; #pragma unroll
;             for (int i = 0; i < 2; ++i) { const int ch = tid + 512 * i; const int r = ch >> 4, c8 = (ch & 15) * 8; *(LAS u32x4*)(B + SB_WD + r * 272 + c8 * 2) = r_wd[i]; *(LAS u32x4*)(B + SB_QD + r * 272 + c8 * 2) = r_qd[i];
;                 const int d = ch >> 3, t8 = (ch & 7) * 8; *(LAS u32x4*)(B + SB_KT + d * 144 + t8 * 2) = r_kt[i]; }
;             { const int r = tid >> 3, s8 = (tid & 7) * 8; *(LAS u32x4*)(B + SB_QK + r * 144 + s8 * 2) = r_qk; }
;             if (tid < 256) *(LAS u32x4*)(B + SB_UB + (tid >> 2) * 64 + (tid & 3) * 16) = r_ub;
;         };
;     ...
;             { u32x2 w; w.x = pk2(sacc[0], sacc[1]); w.y = pk2(sacc[2], sacc[3]); *(LAS u32x2*)(lds + SC_ST + fr * 272 + (wid * 16 + fq * 4) * 2) = w; }
;             if (n + 1 < 32) lstore(cur ^ 1);
.LBB0_1088_o:
	s_xor_b32 s16, s42, 1
	s_mul_i32 s16, s16, 0x10400
	s_nop 4
	v_cvt_pk_bf16_f32 v36, v4, v5
	v_cvt_pk_bf16_f32 v37, v6, v7
	s_add_i32 s16, s16, 0
	ds_write_b64 v106, v[36:37]
	s_and_b64 vcc, exec, s[18:19]
	s_cbranch_vccnz .Lsc2_w47_o
	s_waitcnt vmcnt(8)
	s_branch .Lsc2_wd_o
.Lsc2_w47_o:
	s_waitcnt vmcnt(11)
.Lsc2_wd_o:
	v_add3_u32 v36, s16, v77, v76
	ds_write_b128 v36, v[124:127]
	ds_write_b128 v36, v[128:131] offset:17408
	v_add3_u32 v124, s16, v79, v78
	v_add3_u32 v125, s16, v80, v76
	ds_write_b128 v124, v[132:135] offset:34816
	ds_write_b128 v125, v[136:139]
	ds_write_b128 v125, v[140:143] offset:17408
	v_add3_u32 v125, s16, v81, v78
	ds_write_b128 v125, v[144:147] offset:34816
	ds_write_b128 v124, v[148:151] offset:53248
	s_and_saveexec_b64 s[30:31], s[6:7]
	s_cbranch_execz .LBB0_1079_o
	v_add3_u32 v124, s16, v82, v83
	ds_write_b128 v124, v[152:155] offset:62464
	s_branch .LBB0_1079_o

; __device__ __forceinline__ void scan_phase(const Params& p, int bid, int nblk, LAS unsigned char* lds) {
;     ...
;         auto gload = [&](int n) {
;             const size_t it = (size_t)(bh * 32 + n);
; #pragma unroll
;             for (int i = 0; i < 2; ++i) { const int ch = tid + 512 * i; r_wd[i] = *(const u32x4*)(wdc + it * 8192 + ch * 8); r_qd[i] = *(const u32x4*)(qd + it * 8192 + ch * 8); r_kt[i] = *(const u32x4*)(kt + it * 8192 + ch * 8); }
;             r_qk = *(const u32x4*)(qk + it * 4096 + tid * 8);
;             if (tid < 256) r_ub = *(const u32x4*)(ub + it * 8192 + (tid >> 2) * 128 + sl * 16 + (tid & 3) * 4);
;         };
.Lscan_nw:
	s_and_b64 vcc, exec, s[18:19]
	s_cbranch_vccnz .Lscan_skipld
	v_lshl_add_u64 v[140:141], s[26:27], 0, v[48:49]
	v_add_co_u32_e32 v132, vcc, 0xe541000, v140
	v_lshl_add_u64 v[148:149], s[28:29], 0, v[48:49]
	s_nop 0
	v_addc_co_u32_e32 v133, vcc, 0, v141, vcc
	v_add_co_u32_e32 v134, vcc, 0xf541000, v140
	s_nop 1
	v_addc_co_u32_e32 v135, vcc, 0, v141, vcc
	global_load_dwordx4 v[124:127], v[132:133], off
	global_load_dwordx4 v[128:131], v[134:135], off
	v_add_co_u32_e32 v132, vcc, 0x10541000, v140
	s_nop 1
	v_addc_co_u32_e32 v133, vcc, 0, v141, vcc
	v_add_co_u32_e32 v136, vcc, 0xe543000, v140
	s_nop 1
	v_addc_co_u32_e32 v137, vcc, 0, v141, vcc
	v_add_co_u32_e32 v142, vcc, 0xf543000, v140
	global_load_dwordx4 v[132:135], v[132:133], off
	s_nop 0
	global_load_dwordx4 v[136:139], v[136:137], off
	v_addc_co_u32_e32 v143, vcc, 0, v141, vcc
	v_add_co_u32_e32 v144, vcc, 0x10543000, v140
	s_nop 1
	v_addc_co_u32_e32 v145, vcc, 0, v141, vcc
	global_load_dwordx4 v[140:143], v[142:143], off
	s_nop 0
	global_load_dwordx4 v[144:147], v[144:145], off
	s_nop 0
	v_lshl_add_u64 v[148:149], v[148:149], 0, s[44:45]
	global_load_dwordx4 v[148:151], v[148:149], off
	s_and_saveexec_b64 s[8:9], s[6:7]
	s_cbranch_execz .LBB0_1082
	v_lshl_add_u64 v[152:153], v[72:73], 0, s[22:23]
	global_load_dwordx4 v[152:155], v[152:153], off

; #define LAS __attribute__((address_space(3)))
; __device__ __forceinline__ void scan_phase(const Params& p, int bid, int nblk, LAS unsigned char* lds) {
;     ...
;         auto gload = [&](int n) {
;             const size_t it = (size_t)(bh * 32 + n);
; #pragma unroll
;             for (int i = 0; i < 2; ++i) { const int ch = tid + 512 * i; r_wd[i] = *(const u32x4*)(wdc + it * 8192 + ch * 8); r_qd[i] = *(const u32x4*)(qd + it * 8192 + ch * 8); r_kt[i] = *(const u32x4*)(kt + it * 8192 + ch * 8); }
;             r_qk = *(const u32x4*)(qk + it * 4096 + tid * 8);
;             if (tid < 256) r_ub = *(const u32x4*)(ub + it * 8192 + (tid >> 2) * 128 + sl * 16 + (tid & 3) * 4);
;         };
;     ...
;             if (wid < 4) {
; #pragma unroll
;                 for (int j = 0; j < 4; ++j) acc[j] = *(const LAS float*)(B + SB_UB + ((tw * 16 + fq * 4 + j) * 16 + fr) * 4);
; #pragma unroll
;                 for (int kk = 0; kk < 4; ++kk) { const bf16x8 a = *(const LAS bf16x8*)(B + SB_WD + (tw * 16 + fr) * 272 + (kk * 32 + fq * 8) * 2); const bf16x8 bb = *(const LAS bf16x8*)(lds + SC_ST + fr * 272 + (kk * 32 + fq * 8) * 2);
;                     acc = __builtin_amdgcn_mfma_f32_16x16x32_bf16(a, bb, acc, 0, 0, 0); }
.Lscan_skipld:
	s_and_b32 s42, s35, 1
	s_mul_i32 s8, s42, 0x10400
	v_cndmask_b32_e64 v36, 0, 1, s[18:19]
	s_add_i32 s43, s8, 0
	v_readlane_b32 s16, v69, s35
	v_cmp_ne_u32_e64 s[8:9], 1, v36
	s_andn2_b64 vcc, exec, s[18:19]
	s_mov_b64 s[30:31], -1
	s_cbranch_vccnz .LBB0_1084
	v_add3_u32 v112, s43, v90, v84
	ds_read_b128 v[36:39], v112 offset:17408
	v_add_u32_e32 v116, v86, v84
	ds_read_b128 v[40:43], v112 offset:17472
	ds_read_b128 v[44:47], v116
	ds_read_b128 v[108:111], v116 offset:64
	s_mov_b64 s[30:31], 0
	s_waitcnt lgkmcnt(1)
	v_mfma_f32_16x16x32_bf16 v[36:39], v[36:39], v[44:47], 0
	ds_read_b128 v[44:47], v112 offset:17536
	ds_read_b128 v[112:115], v112 offset:17600
	s_waitcnt lgkmcnt(2)
	v_mfma_f32_16x16x32_bf16 v[36:39], v[40:43], v[108:111], v[36:39]
	ds_read_b128 v[40:43], v116 offset:128
	ds_read_b128 v[108:111], v116 offset:192
	s_waitcnt lgkmcnt(1)
	v_mfma_f32_16x16x32_bf16 v[36:39], v[44:47], v[40:43], v[36:39]
	s_waitcnt lgkmcnt(0)
	v_mfma_f32_16x16x32_bf16 v[36:39], v[112:115], v[108:111], v[36:39]
	v_lshl_add_u64 v[140:141], s[26:27], 0, v[48:49]
	v_add_co_u32_e32 v132, vcc, 0xe541000, v140
	v_lshl_add_u64 v[148:149], s[28:29], 0, v[48:49]
	s_nop 0
	v_addc_co_u32_e32 v133, vcc, 0, v141, vcc
	v_add_co_u32_e32 v134, vcc, 0xf541000, v140
	s_nop 1
	v_addc_co_u32_e32 v135, vcc, 0, v141, vcc
	global_load_dwordx4 v[124:127], v[132:133], off
	global_load_dwordx4 v[128:131], v[134:135], off
	v_add_co_u32_e32 v132, vcc, 0x10541000, v140
	s_nop 1
	v_addc_co_u32_e32 v133, vcc, 0, v141, vcc
	v_add_co_u32_e32 v136, vcc, 0xe543000, v140
	s_nop 1
	v_addc_co_u32_e32 v137, vcc, 0, v141, vcc
	v_add_co_u32_e32 v142, vcc, 0xf543000, v140
	global_load_dwordx4 v[132:135], v[132:133], off
	s_nop 0
	global_load_dwordx4 v[136:139], v[136:137], off
	v_addc_co_u32_e32 v143, vcc, 0, v141, vcc
	v_add_co_u32_e32 v144, vcc, 0x10543000, v140
	s_nop 1
	v_addc_co_u32_e32 v145, vcc, 0, v141, vcc
	global_load_dwordx4 v[140:143], v[142:143], off
	s_nop 0
	global_load_dwordx4 v[144:147], v[144:145], off
	s_nop 0
	v_lshl_add_u64 v[148:149], v[148:149], 0, s[44:45]
	global_load_dwordx4 v[148:151], v[148:149], off

; #define LAS __attribute__((address_space(3)))
; __device__ __forceinline__ void scan_phase(const Params& p, int bid, int nblk, LAS unsigned char* lds) {
;     ...
;         auto lstore = [&](int buf) {
;             LAS unsigned char* B = lds + buf * SB_SIZE;
; #pragma unroll
;             for (int i = 0; i < 2; ++i) { const int ch = tid + 512 * i; const int r = ch >> 4, c8 = (ch & 15) * 8; *(LAS u32x4*)(B + SB_WD + r * 272 + c8 * 2) = r_wd[i]; *(LAS u32x4*)(B + SB_QD + r * 272 + c8 * 2) = r_qd[i];
;                 const int d = ch >> 3, t8 = (ch & 7) * 8; *(LAS u32x4*)(B + SB_KT + d * 144 + t8 * 2) = r_kt[i]; }
;             { const int r = tid >> 3, s8 = (tid & 7) * 8; *(LAS u32x4*)(B + SB_QK + r * 144 + s8 * 2) = r_qk; }
;             if (tid < 256) *(LAS u32x4*)(B + SB_UB + (tid >> 2) * 64 + (tid & 3) * 16) = r_ub;
;         };
.Lsc1_wd:
	v_add3_u32 v36, s16, v77, v76
	ds_write_b128 v36, v[8:11]
	ds_write_b128 v36, v[12:15] offset:17408
	v_add3_u32 v8, s16, v79, v78
	v_add3_u32 v9, s16, v80, v76
	ds_write_b128 v8, v[16:19] offset:34816
	ds_write_b128 v9, v[20:23]
	ds_write_b128 v9, v[24:27] offset:17408
	v_add3_u32 v9, s16, v81, v78
	ds_write_b128 v9, v[28:31] offset:34816
	ds_write_b128 v8, v[32:35] offset:53248
	s_and_saveexec_b64 s[30:31], s[6:7]
	s_cbranch_execz .LBB0_1079
	v_add3_u32 v8, s16, v82, v83
	ds_write_b128 v8, v[0:3] offset:62464
	s_branch .LBB0_1079
